# flash masked softmax: per-element (s>THR ? p : 0) select replaced by one per-row select on the running max; same p, same sum order
# speedup vs baseline: 1.0426x; 1.0031x over previous
.LBB0_864:
	s_nop 0
	v_cndmask_b32_e64 v0, v189, -1, s[0:1]
	v_add_u32_e32 v1, 0xfffffe01, v0
	v_cndmask_b32_e64 v1, v217, v1, s[10:11]
	v_cmp_lt_i32_e32 vcc, -1, v0
	v_cmp_gt_i32_e64 s[2:3], 1, v1
	s_and_b64 vcc, vcc, s[2:3]
	v_cndmask_b32_e32 v2, v215, v96, vcc
	v_cmp_lt_i32_e32 vcc, 0, v0
	v_cmp_gt_i32_e64 s[2:3], 2, v1
	s_and_b64 vcc, vcc, s[2:3]
	v_cndmask_b32_e32 v3, v215, v97, vcc
	v_cmp_lt_i32_e32 vcc, 1, v0
	v_cmp_gt_i32_e64 s[2:3], 3, v1
	s_and_b64 vcc, vcc, s[2:3]
	v_cndmask_b32_e32 v5, v215, v98, vcc
	v_cmp_lt_i32_e32 vcc, 2, v0
	v_cmp_gt_i32_e64 s[2:3], 4, v1
	s_and_b64 vcc, vcc, s[2:3]
	v_cndmask_b32_e32 v6, v215, v99, vcc
	v_cmp_lt_i32_e32 vcc, 7, v0
	v_cmp_gt_i32_e64 s[2:3], 9, v1
	s_and_b64 vcc, vcc, s[2:3]
	v_cndmask_b32_e32 v7, v215, v100, vcc
	v_cmp_lt_i32_e32 vcc, 8, v0
	v_cmp_gt_i32_e64 s[2:3], 10, v1
	s_and_b64 vcc, vcc, s[2:3]
	v_cndmask_b32_e32 v8, v215, v101, vcc
	v_cmp_lt_i32_e32 vcc, 9, v0
	v_cmp_gt_i32_e64 s[2:3], 11, v1
	s_and_b64 vcc, vcc, s[2:3]
	v_cndmask_b32_e32 v9, v215, v102, vcc
	v_cmp_lt_i32_e32 vcc, 10, v0
	v_cmp_gt_i32_e64 s[2:3], 12, v1
	s_and_b64 vcc, vcc, s[2:3]
	v_cndmask_b32_e32 v10, v215, v103, vcc
	v_cmp_lt_i32_e32 vcc, 15, v0
	v_cmp_gt_i32_e64 s[2:3], 17, v1
	s_and_b64 vcc, vcc, s[2:3]
	v_cndmask_b32_e32 v11, v215, v104, vcc
	v_cmp_lt_i32_e32 vcc, 16, v0
	v_cmp_gt_i32_e64 s[2:3], 18, v1
	s_and_b64 vcc, vcc, s[2:3]
	v_cndmask_b32_e32 v12, v215, v105, vcc
	v_cmp_lt_i32_e32 vcc, 17, v0
	v_cmp_gt_i32_e64 s[2:3], 19, v1
	s_and_b64 vcc, vcc, s[2:3]
	v_cndmask_b32_e32 v13, v215, v106, vcc
	v_cmp_lt_i32_e32 vcc, 18, v0
	v_cmp_gt_i32_e64 s[2:3], 20, v1
	s_and_b64 vcc, vcc, s[2:3]
	v_cndmask_b32_e32 v14, v215, v107, vcc
	v_cmp_lt_i32_e32 vcc, 23, v0
	v_cmp_gt_i32_e64 s[2:3], 25, v1
	s_and_b64 vcc, vcc, s[2:3]
	v_cndmask_b32_e32 v15, v215, v108, vcc
	v_cmp_lt_i32_e32 vcc, 24, v0
	v_cmp_gt_i32_e64 s[2:3], 26, v1
	s_and_b64 vcc, vcc, s[2:3]
	v_cndmask_b32_e32 v16, v215, v109, vcc
	v_cmp_lt_i32_e32 vcc, 25, v0
	v_cmp_gt_i32_e64 s[2:3], 27, v1
	s_and_b64 vcc, vcc, s[2:3]
	v_cndmask_b32_e32 v17, v215, v110, vcc
	v_cmp_lt_i32_e32 vcc, 26, v0
	v_cmp_gt_i32_e64 s[2:3], 28, v1
	s_and_b64 vcc, vcc, s[2:3]
	v_cndmask_b32_e32 v18, v215, v111, vcc
	v_cmp_lt_i32_e32 vcc, 31, v0
	v_cmp_gt_i32_e64 s[2:3], 33, v1
	s_and_b64 vcc, vcc, s[2:3]
	v_cndmask_b32_e32 v19, v215, v80, vcc
	v_cmp_lt_i32_e32 vcc, 32, v0
	v_cmp_gt_i32_e64 s[2:3], 34, v1
	s_and_b64 vcc, vcc, s[2:3]
	v_cndmask_b32_e32 v20, v215, v81, vcc
	v_cmp_lt_i32_e32 vcc, 33, v0
	v_cmp_gt_i32_e64 s[2:3], 35, v1
	s_and_b64 vcc, vcc, s[2:3]
	v_cndmask_b32_e32 v21, v215, v82, vcc
	v_cmp_lt_i32_e32 vcc, 34, v0
	v_cmp_gt_i32_e64 s[2:3], 36, v1
	s_and_b64 vcc, vcc, s[2:3]
	v_cndmask_b32_e32 v22, v215, v83, vcc
	v_cmp_lt_i32_e32 vcc, 39, v0
	v_cmp_gt_i32_e64 s[2:3], 41, v1
	s_and_b64 vcc, vcc, s[2:3]
	v_cndmask_b32_e32 v23, v215, v84, vcc
	v_cmp_lt_i32_e32 vcc, 40, v0
	v_cmp_gt_i32_e64 s[2:3], 42, v1
	s_and_b64 vcc, vcc, s[2:3]
	v_cndmask_b32_e32 v24, v215, v85, vcc
	v_cmp_lt_i32_e32 vcc, 41, v0
	v_cmp_gt_i32_e64 s[2:3], 43, v1
	s_and_b64 vcc, vcc, s[2:3]
	v_cndmask_b32_e32 v25, v215, v86, vcc
	v_cmp_lt_i32_e32 vcc, 42, v0
	v_cmp_gt_i32_e64 s[2:3], 44, v1
	s_and_b64 vcc, vcc, s[2:3]
	v_cndmask_b32_e32 v26, v215, v87, vcc
	v_cmp_lt_i32_e32 vcc, 47, v0
	v_cmp_gt_i32_e64 s[2:3], 49, v1
	s_and_b64 vcc, vcc, s[2:3]
	v_max3_f32 v4, v2, s31, v3
	v_cndmask_b32_e32 v27, v215, v88, vcc
	v_cmp_lt_i32_e32 vcc, 48, v0
	v_cmp_gt_i32_e64 s[2:3], 50, v1
	v_max3_f32 v4, v4, v5, v6
	s_and_b64 vcc, vcc, s[2:3]
	v_max3_f32 v4, v4, v7, v8
	v_cndmask_b32_e32 v28, v215, v89, vcc
	v_cmp_lt_i32_e32 vcc, 49, v0
	v_cmp_gt_i32_e64 s[2:3], 51, v1
	v_max3_f32 v4, v4, v9, v10
	s_and_b64 vcc, vcc, s[2:3]
	v_max3_f32 v4, v4, v11, v12
	v_cndmask_b32_e32 v36, v215, v90, vcc
	v_cmp_lt_i32_e32 vcc, 50, v0
	v_cmp_gt_i32_e64 s[2:3], 52, v1
	v_max3_f32 v4, v4, v13, v14
	s_and_b64 vcc, vcc, s[2:3]
	v_max3_f32 v4, v4, v15, v16
	v_cndmask_b32_e32 v37, v215, v91, vcc
	v_cmp_lt_i32_e32 vcc, 55, v0
	v_cmp_gt_i32_e64 s[2:3], 57, v1
	v_max3_f32 v4, v4, v17, v18
	s_and_b64 vcc, vcc, s[2:3]
	v_max3_f32 v4, v4, v19, v20
	v_cndmask_b32_e32 v38, v215, v92, vcc
	v_cmp_lt_i32_e32 vcc, 56, v0
	v_cmp_gt_i32_e64 s[2:3], 58, v1
	v_max3_f32 v4, v4, v21, v22
	s_and_b64 vcc, vcc, s[2:3]
	v_max3_f32 v4, v4, v23, v24
	v_cndmask_b32_e32 v29, v215, v93, vcc
	v_cmp_lt_i32_e32 vcc, 57, v0
	v_cmp_gt_i32_e64 s[2:3], 59, v1
	v_max3_f32 v4, v4, v25, v26
	s_and_b64 vcc, vcc, s[2:3]
	v_max3_f32 v4, v4, v27, v28
	v_cndmask_b32_e32 v30, v215, v94, vcc
	v_cmp_lt_i32_e32 vcc, 58, v0
	v_cmp_gt_i32_e64 s[2:3], 60, v1
	v_max3_f32 v4, v4, v36, v37
	s_and_b64 vcc, vcc, s[2:3]
	v_max3_f32 v4, v4, v38, v29
	v_cndmask_b32_e32 v31, v215, v95, vcc
	v_max3_f32 v0, v4, v30, v31
	ds_bpermute_b32 v1, v165, v0
	s_waitcnt lgkmcnt(0)
	v_max3_f32 v34, v201, v0, v1
	v_cmp_lt_f32_e32 vcc, s33, v34
	v_sub_f32_e32 v32, v201, v34
	v_exp_f32_e32 v32, v32
	v_cndmask_b32_e32 v39, 0, v34, vcc
	v_sub_f32_e32 v0, v2, v39
	v_exp_f32_e32 v0, v0
	v_sub_f32_e32 v1, v3, v39
	v_exp_f32_e32 v1, v1
	v_sub_f32_e32 v2, v5, v39
	v_exp_f32_e32 v2, v2
	v_sub_f32_e32 v3, v6, v39
	v_exp_f32_e32 v3, v3
	v_sub_f32_e32 v4, v7, v39
	v_exp_f32_e32 v4, v4
	v_sub_f32_e32 v5, v8, v39
	v_exp_f32_e32 v5, v5
	v_sub_f32_e32 v6, v9, v39
	v_exp_f32_e32 v6, v6
	v_sub_f32_e32 v7, v10, v39
	v_exp_f32_e32 v7, v7
	v_sub_f32_e32 v8, v11, v39
	v_exp_f32_e32 v8, v8
	v_sub_f32_e32 v9, v12, v39
	v_exp_f32_e32 v9, v9
	v_sub_f32_e32 v10, v13, v39
	v_exp_f32_e32 v10, v10
	v_sub_f32_e32 v11, v14, v39
	v_exp_f32_e32 v11, v11
	v_sub_f32_e32 v12, v15, v39
	v_exp_f32_e32 v12, v12
	v_sub_f32_e32 v13, v16, v39
	v_exp_f32_e32 v13, v13
	v_sub_f32_e32 v14, v17, v39
	v_exp_f32_e32 v14, v14
	v_sub_f32_e32 v15, v18, v39
	v_exp_f32_e32 v15, v15
	v_sub_f32_e32 v16, v19, v39
	v_exp_f32_e32 v16, v16
	v_sub_f32_e32 v17, v20, v39
	v_exp_f32_e32 v17, v17
	v_sub_f32_e32 v18, v21, v39
	v_exp_f32_e32 v18, v18
	v_sub_f32_e32 v19, v22, v39
	v_exp_f32_e32 v19, v19
	v_sub_f32_e32 v20, v23, v39
	v_exp_f32_e32 v20, v20
	v_sub_f32_e32 v21, v24, v39
	v_exp_f32_e32 v21, v21
	v_sub_f32_e32 v22, v25, v39
	v_exp_f32_e32 v22, v22
	v_sub_f32_e32 v23, v26, v39
	v_exp_f32_e32 v23, v23
	v_sub_f32_e32 v24, v27, v39
	v_exp_f32_e32 v24, v24
	v_sub_f32_e32 v25, v28, v39
	v_exp_f32_e32 v25, v25
	v_sub_f32_e32 v26, v36, v39
	v_exp_f32_e32 v26, v26
	v_sub_f32_e32 v27, v37, v39
	v_exp_f32_e32 v27, v27
	v_sub_f32_e32 v28, v38, v39
	v_exp_f32_e32 v28, v28
	v_sub_f32_e32 v29, v29, v39
	v_exp_f32_e32 v29, v29
	v_sub_f32_e32 v30, v30, v39
	v_exp_f32_e32 v30, v30
	v_sub_f32_e32 v31, v31, v39
	v_exp_f32_e32 v31, v31
	v_add_f32_e32 v36, 0, v0
	v_add_f32_e32 v36, v1, v36
	v_add_f32_e32 v36, v2, v36
	v_add_f32_e32 v36, v3, v36
	v_add_f32_e32 v36, v4, v36
	v_add_f32_e32 v36, v5, v36
	v_add_f32_e32 v36, v6, v36
	v_add_f32_e32 v36, v7, v36
	v_add_f32_e32 v36, v8, v36
	v_add_f32_e32 v36, v9, v36
	v_add_f32_e32 v36, v10, v36
	v_add_f32_e32 v36, v11, v36
	v_add_f32_e32 v36, v12, v36
	v_add_f32_e32 v36, v13, v36
	v_add_f32_e32 v36, v14, v36
	v_add_f32_e32 v36, v15, v36
	v_add_f32_e32 v36, v16, v36
	v_add_f32_e32 v36, v17, v36
	v_add_f32_e32 v36, v18, v36
	v_add_f32_e32 v36, v19, v36
	v_add_f32_e32 v36, v20, v36
	v_add_f32_e32 v36, v21, v36
	v_add_f32_e32 v36, v22, v36
	v_add_f32_e32 v36, v23, v36
	v_add_f32_e32 v36, v24, v36
	v_add_f32_e32 v36, v25, v36
	v_add_f32_e32 v36, v26, v36
	v_add_f32_e32 v36, v27, v36
	v_add_f32_e32 v36, v28, v36
	v_add_f32_e32 v36, v29, v36
	v_add_f32_e32 v36, v30, v36
	v_add_f32_e32 v36, v31, v36
	v_fmac_f32_e32 v36, v202, v32
	s_cbranch_execnz .LBB0_859

.LBB0_866:
	v_subrev_u32_e32 v0, 64, v189
	v_cndmask_b32_e64 v0, v0, -1, s[0:1]
	v_add_u32_e32 v1, 0xfffffe01, v0
	v_cndmask_b32_e64 v1, v217, v1, s[10:11]
	v_cmp_lt_i32_e32 vcc, -1, v0
	v_cmp_gt_i32_e64 s[2:3], 1, v1
	s_and_b64 vcc, vcc, s[2:3]
	v_cndmask_b32_e32 v2, v215, v96, vcc
	v_cmp_lt_i32_e32 vcc, 0, v0
	v_cmp_gt_i32_e64 s[2:3], 2, v1
	s_and_b64 vcc, vcc, s[2:3]
	v_cndmask_b32_e32 v3, v215, v97, vcc
	v_cmp_lt_i32_e32 vcc, 1, v0
	v_cmp_gt_i32_e64 s[2:3], 3, v1
	s_and_b64 vcc, vcc, s[2:3]
	v_cndmask_b32_e32 v5, v215, v98, vcc
	v_cmp_lt_i32_e32 vcc, 2, v0
	v_cmp_gt_i32_e64 s[2:3], 4, v1
	s_and_b64 vcc, vcc, s[2:3]
	v_cndmask_b32_e32 v6, v215, v99, vcc
	v_cmp_lt_i32_e32 vcc, 7, v0
	v_cmp_gt_i32_e64 s[2:3], 9, v1
	s_and_b64 vcc, vcc, s[2:3]
	v_cndmask_b32_e32 v7, v215, v100, vcc
	v_cmp_lt_i32_e32 vcc, 8, v0
	v_cmp_gt_i32_e64 s[2:3], 10, v1
	s_and_b64 vcc, vcc, s[2:3]
	v_cndmask_b32_e32 v8, v215, v101, vcc
	v_cmp_lt_i32_e32 vcc, 9, v0
	v_cmp_gt_i32_e64 s[2:3], 11, v1
	s_and_b64 vcc, vcc, s[2:3]
	v_cndmask_b32_e32 v9, v215, v102, vcc
	v_cmp_lt_i32_e32 vcc, 10, v0
	v_cmp_gt_i32_e64 s[2:3], 12, v1
	s_and_b64 vcc, vcc, s[2:3]
	v_cndmask_b32_e32 v10, v215, v103, vcc
	v_cmp_lt_i32_e32 vcc, 15, v0
	v_cmp_gt_i32_e64 s[2:3], 17, v1
	s_and_b64 vcc, vcc, s[2:3]
	v_cndmask_b32_e32 v11, v215, v104, vcc
	v_cmp_lt_i32_e32 vcc, 16, v0
	v_cmp_gt_i32_e64 s[2:3], 18, v1
	s_and_b64 vcc, vcc, s[2:3]
	v_cndmask_b32_e32 v12, v215, v105, vcc
	v_cmp_lt_i32_e32 vcc, 17, v0
	v_cmp_gt_i32_e64 s[2:3], 19, v1
	s_and_b64 vcc, vcc, s[2:3]
	v_cndmask_b32_e32 v13, v215, v106, vcc
	v_cmp_lt_i32_e32 vcc, 18, v0
	v_cmp_gt_i32_e64 s[2:3], 20, v1
	s_and_b64 vcc, vcc, s[2:3]
	v_cndmask_b32_e32 v14, v215, v107, vcc
	v_cmp_lt_i32_e32 vcc, 23, v0
	v_cmp_gt_i32_e64 s[2:3], 25, v1
	s_and_b64 vcc, vcc, s[2:3]
	v_cndmask_b32_e32 v15, v215, v108, vcc
	v_cmp_lt_i32_e32 vcc, 24, v0
	v_cmp_gt_i32_e64 s[2:3], 26, v1
	s_and_b64 vcc, vcc, s[2:3]
	v_cndmask_b32_e32 v16, v215, v109, vcc
	v_cmp_lt_i32_e32 vcc, 25, v0
	v_cmp_gt_i32_e64 s[2:3], 27, v1
	s_and_b64 vcc, vcc, s[2:3]
	v_cndmask_b32_e32 v17, v215, v110, vcc
	v_cmp_lt_i32_e32 vcc, 26, v0
	v_cmp_gt_i32_e64 s[2:3], 28, v1
	s_and_b64 vcc, vcc, s[2:3]
	v_cndmask_b32_e32 v18, v215, v111, vcc
	v_cmp_lt_i32_e32 vcc, 31, v0
	v_cmp_gt_i32_e64 s[2:3], 33, v1
	s_and_b64 vcc, vcc, s[2:3]
	v_cndmask_b32_e32 v19, v215, v80, vcc
	v_cmp_lt_i32_e32 vcc, 32, v0
	v_cmp_gt_i32_e64 s[2:3], 34, v1
	s_and_b64 vcc, vcc, s[2:3]
	v_cndmask_b32_e32 v20, v215, v81, vcc
	v_cmp_lt_i32_e32 vcc, 33, v0
	v_cmp_gt_i32_e64 s[2:3], 35, v1
	s_and_b64 vcc, vcc, s[2:3]
	v_cndmask_b32_e32 v21, v215, v82, vcc
	v_cmp_lt_i32_e32 vcc, 34, v0
	v_cmp_gt_i32_e64 s[2:3], 36, v1
	s_and_b64 vcc, vcc, s[2:3]
	v_cndmask_b32_e32 v22, v215, v83, vcc
	v_cmp_lt_i32_e32 vcc, 39, v0
	v_cmp_gt_i32_e64 s[2:3], 41, v1
	s_and_b64 vcc, vcc, s[2:3]
	v_cndmask_b32_e32 v23, v215, v84, vcc
	v_cmp_lt_i32_e32 vcc, 40, v0
	v_cmp_gt_i32_e64 s[2:3], 42, v1
	s_and_b64 vcc, vcc, s[2:3]
	v_cndmask_b32_e32 v24, v215, v85, vcc
	v_cmp_lt_i32_e32 vcc, 41, v0
	v_cmp_gt_i32_e64 s[2:3], 43, v1
	s_and_b64 vcc, vcc, s[2:3]
	v_cndmask_b32_e32 v25, v215, v86, vcc
	v_cmp_lt_i32_e32 vcc, 42, v0
	v_cmp_gt_i32_e64 s[2:3], 44, v1
	s_and_b64 vcc, vcc, s[2:3]
	v_cndmask_b32_e32 v26, v215, v87, vcc
	v_cmp_lt_i32_e32 vcc, 47, v0
	v_cmp_gt_i32_e64 s[2:3], 49, v1
	s_and_b64 vcc, vcc, s[2:3]
	v_max3_f32 v4, v2, s31, v3
	v_cndmask_b32_e32 v27, v215, v88, vcc
	v_cmp_lt_i32_e32 vcc, 48, v0
	v_cmp_gt_i32_e64 s[2:3], 50, v1
	v_max3_f32 v4, v4, v5, v6
	s_and_b64 vcc, vcc, s[2:3]
	v_max3_f32 v4, v4, v7, v8
	v_cndmask_b32_e32 v28, v215, v89, vcc
	v_cmp_lt_i32_e32 vcc, 49, v0
	v_cmp_gt_i32_e64 s[2:3], 51, v1
	v_max3_f32 v4, v4, v9, v10
	s_and_b64 vcc, vcc, s[2:3]
	v_max3_f32 v4, v4, v11, v12
	v_cndmask_b32_e32 v35, v215, v90, vcc
	v_cmp_lt_i32_e32 vcc, 50, v0
	v_cmp_gt_i32_e64 s[2:3], 52, v1
	v_max3_f32 v4, v4, v13, v14
	s_and_b64 vcc, vcc, s[2:3]
	v_max3_f32 v4, v4, v15, v16
	v_cndmask_b32_e32 v39, v215, v91, vcc
	v_cmp_lt_i32_e32 vcc, 55, v0
	v_cmp_gt_i32_e64 s[2:3], 57, v1
	v_max3_f32 v4, v4, v17, v18
	s_and_b64 vcc, vcc, s[2:3]
	v_max3_f32 v4, v4, v19, v20
	v_cndmask_b32_e32 v40, v215, v92, vcc
	v_cmp_lt_i32_e32 vcc, 56, v0
	v_cmp_gt_i32_e64 s[2:3], 58, v1
	v_max3_f32 v4, v4, v21, v22
	s_and_b64 vcc, vcc, s[2:3]
	v_max3_f32 v4, v4, v23, v24
	v_cndmask_b32_e32 v29, v215, v93, vcc
	v_cmp_lt_i32_e32 vcc, 57, v0
	v_cmp_gt_i32_e64 s[2:3], 59, v1
	v_max3_f32 v4, v4, v25, v26
	s_and_b64 vcc, vcc, s[2:3]
	v_max3_f32 v4, v4, v27, v28
	v_cndmask_b32_e32 v30, v215, v94, vcc
	v_cmp_lt_i32_e32 vcc, 58, v0
	v_cmp_gt_i32_e64 s[2:3], 60, v1
	v_max3_f32 v4, v4, v35, v39
	s_and_b64 vcc, vcc, s[2:3]
	v_max3_f32 v4, v4, v40, v29
	v_cndmask_b32_e32 v31, v215, v95, vcc
	v_max3_f32 v0, v4, v30, v31
	ds_bpermute_b32 v1, v165, v0
	s_waitcnt lgkmcnt(0)
	v_max3_f32 v201, v34, v0, v1
	v_cmp_lt_f32_e32 vcc, s33, v201
	v_sub_f32_e32 v32, v34, v201
	v_exp_f32_e32 v32, v32
	v_cndmask_b32_e32 v34, 0, v201, vcc
	v_sub_f32_e32 v0, v2, v34
	v_exp_f32_e32 v0, v0
	v_sub_f32_e32 v1, v3, v34
	v_exp_f32_e32 v1, v1
	v_sub_f32_e32 v2, v5, v34
	v_exp_f32_e32 v2, v2
	v_sub_f32_e32 v3, v6, v34
	v_exp_f32_e32 v3, v3
	v_sub_f32_e32 v4, v7, v34
	v_exp_f32_e32 v4, v4
	v_sub_f32_e32 v5, v8, v34
	v_exp_f32_e32 v5, v5
	v_sub_f32_e32 v6, v9, v34
	v_exp_f32_e32 v6, v6
	v_sub_f32_e32 v7, v10, v34
	v_exp_f32_e32 v7, v7
	v_sub_f32_e32 v8, v11, v34
	v_exp_f32_e32 v8, v8
	v_sub_f32_e32 v9, v12, v34
	v_exp_f32_e32 v9, v9
	v_sub_f32_e32 v10, v13, v34
	v_exp_f32_e32 v10, v10
	v_sub_f32_e32 v11, v14, v34
	v_exp_f32_e32 v11, v11
	v_sub_f32_e32 v12, v15, v34
	v_exp_f32_e32 v12, v12
	v_sub_f32_e32 v13, v16, v34
	v_exp_f32_e32 v13, v13
	v_sub_f32_e32 v14, v17, v34
	v_exp_f32_e32 v14, v14
	v_sub_f32_e32 v15, v18, v34
	v_exp_f32_e32 v15, v15
	v_sub_f32_e32 v16, v19, v34
	v_exp_f32_e32 v16, v16
	v_sub_f32_e32 v17, v20, v34
	v_exp_f32_e32 v17, v17
	v_sub_f32_e32 v18, v21, v34
	v_exp_f32_e32 v18, v18
	v_sub_f32_e32 v19, v22, v34
	v_exp_f32_e32 v19, v19
	v_sub_f32_e32 v20, v23, v34
	v_exp_f32_e32 v20, v20
	v_sub_f32_e32 v21, v24, v34
	v_exp_f32_e32 v21, v21
	v_sub_f32_e32 v22, v25, v34
	v_exp_f32_e32 v22, v22
	v_sub_f32_e32 v23, v26, v34
	v_exp_f32_e32 v23, v23
	v_sub_f32_e32 v24, v27, v34
	v_exp_f32_e32 v24, v24
	v_sub_f32_e32 v25, v28, v34
	v_exp_f32_e32 v25, v25
	v_sub_f32_e32 v26, v35, v34
	v_exp_f32_e32 v26, v26
	v_sub_f32_e32 v27, v39, v34
	v_exp_f32_e32 v27, v27
	v_sub_f32_e32 v28, v40, v34
	v_exp_f32_e32 v28, v28
	v_sub_f32_e32 v29, v29, v34
	v_exp_f32_e32 v29, v29
	v_sub_f32_e32 v30, v30, v34
	v_exp_f32_e32 v30, v30
	v_sub_f32_e32 v31, v31, v34
	v_exp_f32_e32 v31, v31
	v_add_f32_e32 v35, 0, v0
	v_add_f32_e32 v35, v1, v35
	v_add_f32_e32 v35, v2, v35
	v_add_f32_e32 v35, v3, v35
	v_add_f32_e32 v35, v4, v35
	v_add_f32_e32 v35, v5, v35
	v_add_f32_e32 v35, v6, v35
	v_add_f32_e32 v35, v7, v35
	v_add_f32_e32 v35, v8, v35
	v_add_f32_e32 v35, v9, v35
	v_add_f32_e32 v35, v10, v35
	v_add_f32_e32 v35, v11, v35
	v_add_f32_e32 v35, v12, v35
	v_add_f32_e32 v35, v13, v35
	v_add_f32_e32 v35, v14, v35
	v_add_f32_e32 v35, v15, v35
	v_add_f32_e32 v35, v16, v35
	v_add_f32_e32 v35, v17, v35
	v_add_f32_e32 v35, v18, v35
	v_add_f32_e32 v35, v19, v35
	v_add_f32_e32 v35, v20, v35
	v_add_f32_e32 v35, v21, v35
	v_add_f32_e32 v35, v22, v35
	v_add_f32_e32 v35, v23, v35
	v_add_f32_e32 v35, v24, v35
	v_add_f32_e32 v35, v25, v35
	v_add_f32_e32 v35, v26, v35
	v_add_f32_e32 v35, v27, v35
	v_add_f32_e32 v35, v28, v35
	v_add_f32_e32 v35, v29, v35
	v_add_f32_e32 v35, v30, v35
	v_add_f32_e32 v202, v31, v35
	v_fmac_f32_e32 v202, v36, v32
	s_cbranch_execnz .LBB0_863
